# v3: EpiRes hand epilogue + acc zeroing with v_mov_b64 + removed header vmcnt(0) in out-proj GEMM
# baseline (speedup 1.0000x reference)
; template <class Epi>
; __device__ __forceinline__ void gemm_phase(LAS unsigned char* lds, const Gemm g, const StaticOrder& S, const Epi& E, int wv) {
;     ...
;         const bool has_next = S.next(ui + 1, nxt);
;         const char* nA = has_next ? (const char*)g.A + (size_t)nxt.pm * tstep : cA; const char* nB = has_next ? (const char*)g.Bt + (size_t)nxt.pn * tstep : cB;
;     ...
; #pragma unroll
;         for (int a = 0; a < 2; ++a)
; #pragma unroll
;             for (int b = 0; b < 2; ++b)
; #pragma unroll
;                 for (int m = 0; m < 4; ++m)
; #pragma unroll
;                     for (int n = 0; n < 2; ++n) acc[a][b][m][n] = (f32x4){0.f, 0.f, 0.f, 0.f};
.LBB0_221:
	v_mov_b64_e32 v[0:1], 0xb00
	s_ashr_i32 s77, s76, 31
	v_cmp_lt_i64_e32 vcc, s[12:13], v[0:1]
	s_lshl_b64 s[12:13], s[76:77], 19
	v_readlane_b32 s20, v255, 12
	v_readlane_b32 s21, v255, 13
	s_add_u32 s78, s20, s12
	s_addc_u32 s79, s21, s13
	s_and_b64 s[12:13], vcc, exec
	s_cselect_b32 s34, s79, s9
	s_cselect_b32 s35, s78, s8
	s_ashr_i32 s73, s72, 31
	s_lshl_b64 s[12:13], s[72:73], 19
	s_add_u32 s62, s3, s12
	s_addc_u32 s63, s14, s13
	s_and_b64 s[12:13], vcc, exec
	s_cselect_b32 s64, s63, s11
	s_cselect_b32 s65, s62, s10
	s_add_u32 s8, s8, 0x40080
	s_addc_u32 s9, s9, 0
	s_add_u32 s73, s10, 0x100
	v_mov_b64_e32 v[0:1], 0
	v_mov_b64_e32 v[2:3], 0
	v_mov_b64_e32 v[4:5], 0
	v_mov_b64_e32 v[6:7], 0
	v_mov_b64_e32 v[8:9], 0
	v_mov_b64_e32 v[10:11], 0
	v_mov_b64_e32 v[12:13], 0
	v_mov_b64_e32 v[14:15], 0
	v_mov_b64_e32 v[16:17], 0
	v_mov_b64_e32 v[18:19], 0
	v_mov_b64_e32 v[20:21], 0
	v_mov_b64_e32 v[22:23], 0
	v_mov_b64_e32 v[24:25], 0
	v_mov_b64_e32 v[26:27], 0
	v_mov_b64_e32 v[28:29], 0
	v_mov_b64_e32 v[30:31], 0
	v_mov_b64_e32 v[32:33], 0
	v_mov_b64_e32 v[34:35], 0
	v_mov_b64_e32 v[36:37], 0
	v_mov_b64_e32 v[38:39], 0
	v_mov_b64_e32 v[40:41], 0
	v_mov_b64_e32 v[42:43], 0
	v_mov_b64_e32 v[44:45], 0
	v_mov_b64_e32 v[46:47], 0
	v_mov_b64_e32 v[48:49], 0
	v_mov_b64_e32 v[50:51], 0
	v_mov_b64_e32 v[52:53], 0
	v_mov_b64_e32 v[54:55], 0
	v_mov_b64_e32 v[56:57], 0
	v_mov_b64_e32 v[58:59], 0
	v_mov_b64_e32 v[60:61], 0
	v_mov_b64_e32 v[62:63], 0
	v_mov_b64_e32 v[64:65], 0
	v_mov_b64_e32 v[66:67], 0
	v_mov_b64_e32 v[68:69], 0
	v_mov_b64_e32 v[70:71], 0
	v_mov_b64_e32 v[72:73], 0
	v_mov_b64_e32 v[74:75], 0
	v_mov_b64_e32 v[76:77], 0
	v_mov_b64_e32 v[78:79], 0
	v_mov_b64_e32 v[80:81], 0
	v_mov_b64_e32 v[82:83], 0
	v_mov_b64_e32 v[84:85], 0
	v_mov_b64_e32 v[86:87], 0
	v_mov_b64_e32 v[88:89], 0
	v_mov_b64_e32 v[90:91], 0
	v_mov_b64_e32 v[92:93], 0
	v_mov_b64_e32 v[94:95], 0
	v_mov_b64_e32 v[96:97], 0
	v_mov_b64_e32 v[98:99], 0
	v_mov_b64_e32 v[100:101], 0
	v_mov_b64_e32 v[102:103], 0
	v_mov_b64_e32 v[104:105], 0
	v_mov_b64_e32 v[106:107], 0
	v_mov_b64_e32 v[108:109], 0
	v_mov_b64_e32 v[110:111], 0
	v_mov_b64_e32 v[112:113], 0
	v_mov_b64_e32 v[114:115], 0
	v_mov_b64_e32 v[116:117], 0
	v_mov_b64_e32 v[118:119], 0
	v_mov_b64_e32 v[120:121], 0
	v_mov_b64_e32 v[122:123], 0
	v_mov_b64_e32 v[124:125], 0
	v_mov_b64_e32 v[126:127], 0
	s_addc_u32 s77, s11, 0
	s_mov_b32 s85, -2

; template <class Epi>
; __device__ __forceinline__ void gemm_phase(LAS unsigned char* lds, const Gemm g, const StaticOrder& S, const Epi& E, int wv) {
;     ...
;         const bool has_next = S.next(ui + 1, nxt);
;         const char* nA = has_next ? (const char*)g.A + (size_t)nxt.pm * tstep : cA; const char* nB = has_next ? (const char*)g.Bt + (size_t)nxt.pn * tstep : cB;
;     ...
; #pragma unroll
;         for (int a = 0; a < 2; ++a)
; #pragma unroll
;             for (int b = 0; b < 2; ++b)
; #pragma unroll
;                 for (int m = 0; m < 4; ++m)
; #pragma unroll
;                     for (int n = 0; n < 2; ++n) acc[a][b][m][n] = (f32x4){0.f, 0.f, 0.f, 0.f};
.LBB0_423:
	v_mov_b64_e32 v[0:1], 0x400
	s_ashr_i32 s61, s60, 31
	v_cmp_lt_i64_e32 vcc, s[8:9], v[0:1]
	s_lshl_b64 s[8:9], s[60:61], 20
	s_add_u32 s62, s2, s8
	s_addc_u32 s63, s3, s9
	s_and_b64 s[8:9], vcc, exec
	s_cselect_b32 s34, s63, s71
	s_cselect_b32 s35, s62, s70
	s_ashr_i32 s59, s58, 31
	s_lshl_b64 s[8:9], s[58:59], 20
	s_add_u32 s68, s14, s8
	s_addc_u32 s69, s15, s9
	s_and_b64 s[8:9], vcc, exec
	s_cselect_b32 s59, s69, s65
	s_cselect_b32 s61, s68, s64
	s_add_u32 s8, s70, 0x80080
	s_addc_u32 s9, s71, 0
	s_add_u32 s79, s64, 0x100
	v_mov_b64_e32 v[0:1], 0
	v_mov_b64_e32 v[2:3], 0
	v_mov_b64_e32 v[4:5], 0
	v_mov_b64_e32 v[6:7], 0
	v_mov_b64_e32 v[8:9], 0
	v_mov_b64_e32 v[10:11], 0
	v_mov_b64_e32 v[12:13], 0
	v_mov_b64_e32 v[14:15], 0
	v_mov_b64_e32 v[16:17], 0
	v_mov_b64_e32 v[18:19], 0
	v_mov_b64_e32 v[20:21], 0
	v_mov_b64_e32 v[22:23], 0
	v_mov_b64_e32 v[24:25], 0
	v_mov_b64_e32 v[26:27], 0
	v_mov_b64_e32 v[28:29], 0
	v_mov_b64_e32 v[30:31], 0
	v_mov_b64_e32 v[32:33], 0
	v_mov_b64_e32 v[34:35], 0
	v_mov_b64_e32 v[36:37], 0
	v_mov_b64_e32 v[38:39], 0
	v_mov_b64_e32 v[40:41], 0
	v_mov_b64_e32 v[42:43], 0
	v_mov_b64_e32 v[44:45], 0
	v_mov_b64_e32 v[46:47], 0
	v_mov_b64_e32 v[48:49], 0
	v_mov_b64_e32 v[50:51], 0
	v_mov_b64_e32 v[52:53], 0
	v_mov_b64_e32 v[54:55], 0
	v_mov_b64_e32 v[56:57], 0
	v_mov_b64_e32 v[58:59], 0
	v_mov_b64_e32 v[60:61], 0
	v_mov_b64_e32 v[62:63], 0
	v_mov_b64_e32 v[64:65], 0
	v_mov_b64_e32 v[66:67], 0
	v_mov_b64_e32 v[68:69], 0
	v_mov_b64_e32 v[70:71], 0
	v_mov_b64_e32 v[72:73], 0
	v_mov_b64_e32 v[74:75], 0
	v_mov_b64_e32 v[76:77], 0
	v_mov_b64_e32 v[78:79], 0
	v_mov_b64_e32 v[80:81], 0
	v_mov_b64_e32 v[82:83], 0
	v_mov_b64_e32 v[84:85], 0
	v_mov_b64_e32 v[86:87], 0
	v_mov_b64_e32 v[88:89], 0
	v_mov_b64_e32 v[90:91], 0
	v_mov_b64_e32 v[92:93], 0
	v_mov_b64_e32 v[94:95], 0
	v_mov_b64_e32 v[96:97], 0
	v_mov_b64_e32 v[98:99], 0
	v_mov_b64_e32 v[100:101], 0
	v_mov_b64_e32 v[102:103], 0
	v_mov_b64_e32 v[104:105], 0
	v_mov_b64_e32 v[106:107], 0
	v_mov_b64_e32 v[108:109], 0
	v_mov_b64_e32 v[110:111], 0
	v_mov_b64_e32 v[112:113], 0
	v_mov_b64_e32 v[114:115], 0
	v_mov_b64_e32 v[116:117], 0
	v_mov_b64_e32 v[118:119], 0
	v_mov_b64_e32 v[120:121], 0
	v_mov_b64_e32 v[122:123], 0
	v_mov_b64_e32 v[124:125], 0
	v_mov_b64_e32 v[126:127], 0
	s_addc_u32 s85, s65, 0
	s_mov_b32 s86, -2

; template <class Epi>
; __device__ __forceinline__ void gemm_phase(LAS unsigned char* lds, const Gemm g, const StaticOrder& S, const Epi& E, int wv) {
;     ...
;         const bool has_next = S.next(ui + 1, nxt);
;         const char* nA = has_next ? (const char*)g.A + (size_t)nxt.pm * tstep : cA; const char* nB = has_next ? (const char*)g.Bt + (size_t)nxt.pn * tstep : cB;
;     ...
; #pragma unroll
;         for (int a = 0; a < 2; ++a)
; #pragma unroll
;             for (int b = 0; b < 2; ++b)
; #pragma unroll
;                 for (int m = 0; m < 4; ++m)
; #pragma unroll
;                     for (int n = 0; n < 2; ++n) acc[a][b][m][n] = (f32x4){0.f, 0.f, 0.f, 0.f};
.LBB0_633:
	s_ashr_i32 s13, s12, 31
	v_cmp_lt_i64_e32 vcc, s[14:15], v[250:251]
	s_lshl_b64 s[14:15], s[12:13], 19
	v_readlane_b32 s16, v255, 12
	v_readlane_b32 s17, v255, 13
	s_add_u32 s14, s16, s14
	s_addc_u32 s15, s17, s15
	s_and_b64 s[16:17], vcc, exec
	s_cselect_b32 s13, s15, s19
	s_cselect_b32 s59, s14, s18
	s_ashr_i32 s11, s10, 31
	s_lshl_b64 s[16:17], s[10:11], 19
	s_add_u32 s16, s2, s16
	s_addc_u32 s17, s3, s17
	s_and_b64 s[22:23], vcc, exec
	s_cselect_b32 s11, s17, s21
	s_cselect_b32 s60, s16, s20
	s_add_u32 s18, s18, 0x40080
	s_addc_u32 s19, s19, 0
	s_add_u32 s61, s20, 0x100
	v_mov_b64_e32 v[0:1], 0
	v_mov_b64_e32 v[2:3], 0
	v_mov_b64_e32 v[4:5], 0
	v_mov_b64_e32 v[6:7], 0
	v_mov_b64_e32 v[8:9], 0
	v_mov_b64_e32 v[10:11], 0
	v_mov_b64_e32 v[12:13], 0
	v_mov_b64_e32 v[14:15], 0
	v_mov_b64_e32 v[16:17], 0
	v_mov_b64_e32 v[18:19], 0
	v_mov_b64_e32 v[20:21], 0
	v_mov_b64_e32 v[22:23], 0
	v_mov_b64_e32 v[24:25], 0
	v_mov_b64_e32 v[26:27], 0
	v_mov_b64_e32 v[28:29], 0
	v_mov_b64_e32 v[30:31], 0
	v_mov_b64_e32 v[32:33], 0
	v_mov_b64_e32 v[34:35], 0
	v_mov_b64_e32 v[36:37], 0
	v_mov_b64_e32 v[38:39], 0
	v_mov_b64_e32 v[40:41], 0
	v_mov_b64_e32 v[42:43], 0
	v_mov_b64_e32 v[44:45], 0
	v_mov_b64_e32 v[46:47], 0
	v_mov_b64_e32 v[48:49], 0
	v_mov_b64_e32 v[50:51], 0
	v_mov_b64_e32 v[52:53], 0
	v_mov_b64_e32 v[54:55], 0
	v_mov_b64_e32 v[56:57], 0
	v_mov_b64_e32 v[58:59], 0
	v_mov_b64_e32 v[60:61], 0
	v_mov_b64_e32 v[62:63], 0
	v_mov_b64_e32 v[64:65], 0
	v_mov_b64_e32 v[66:67], 0
	v_mov_b64_e32 v[68:69], 0
	v_mov_b64_e32 v[70:71], 0
	v_mov_b64_e32 v[72:73], 0
	v_mov_b64_e32 v[74:75], 0
	v_mov_b64_e32 v[76:77], 0
	v_mov_b64_e32 v[78:79], 0
	v_mov_b64_e32 v[80:81], 0
	v_mov_b64_e32 v[82:83], 0
	v_mov_b64_e32 v[84:85], 0
	v_mov_b64_e32 v[86:87], 0
	v_mov_b64_e32 v[88:89], 0
	v_mov_b64_e32 v[90:91], 0
	v_mov_b64_e32 v[92:93], 0
	v_mov_b64_e32 v[94:95], 0
	v_mov_b64_e32 v[96:97], 0
	v_mov_b64_e32 v[98:99], 0
	v_mov_b64_e32 v[100:101], 0
	v_mov_b64_e32 v[102:103], 0
	v_mov_b64_e32 v[104:105], 0
	v_mov_b64_e32 v[106:107], 0
	v_mov_b64_e32 v[108:109], 0
	v_mov_b64_e32 v[110:111], 0
	v_mov_b64_e32 v[112:113], 0
	v_mov_b64_e32 v[114:115], 0
	v_mov_b64_e32 v[116:117], 0
	v_mov_b64_e32 v[118:119], 0
	v_mov_b64_e32 v[120:121], 0
	v_mov_b64_e32 v[122:123], 0
	v_mov_b64_e32 v[124:125], 0
	v_mov_b64_e32 v[126:127], 0
	s_addc_u32 s62, s21, 0
	s_mov_b32 s63, -2
